# hg<true>: next chunk's decay totals published before barrier d (MFMA shadow); barrier a moved after the OS reads; LF loads first
# speedup vs baseline: 1.0006x; 1.0006x over previous
; #define LAS __attribute__((address_space(3)))
; __device__ __forceinline__ unsigned pk2(float lo, float hi) { typedef float f2v __attribute__((ext_vector_type(2))); typedef __bf16 b2v __attribute__((ext_vector_type(2))); const f2v v = {lo, hi}; const b2v b = __builtin_convertvector(v, b2v); return __builtin_bit_cast(unsigned, b); }
; #define lane lane_id()
; template <bool FULL, bool STORE = true>
; __device__ __forceinline__ void hg_item(const Prm& P, LAS unsigned char* lds, int item, int wave) {
;     unsigned char* ws = P.ws; const int lane = lane_id(), tid = wave * 64 + lane;
;     const int b = item >> 6, h = (item >> 3) & 7, seg = item & 7;
;     const int l31 = lane & 31, lh = lane >> 5;
;     const int k2 = lane * 2, tg = wave;
;     const int kb = wave >> 1, vb0 = (wave & 1) * 2;
;     const _Float16* LF = (const _Float16*)P.out; const bf16_t* Q = (const bf16_t*)(ws + WS_Q); const bf16_t* IV = (const bf16_t*)(ws + WS_IV); const bf16_t* GH = (const bf16_t*)(ws + WS_GH);
;     bf16_t* AHG = (bf16_t*)(ws + WS_AHG);
;     float* AGG = (float*)(ws + WS_HGAGG); float* DEC = (float*)(ws + WS_HGDEC);
;     f32x16 S[2];
; #pragma unroll
;     for (int i = 0; i < 2; ++i)
; #pragma unroll
;         for (int r = 0; r < 16; ++r) S[i][r] = 0.f;
;     float sumlog0 = 0.f, sumlog1 = 0.f;
;     if (FULL) {
;         for (int s2 = 0; s2 < seg; ++s2) { const int it2 = item - seg + s2;
; #pragma unroll
;             for (int g4 = 0; g4 < 4; ++g4) { const f32x4 d = *(const f32x4*)(DEC + it2 * 128 + kb * 32 + 8 * g4 + 4 * lh);
; #pragma unroll
;                 for (int i = 0; i < 2; ++i)
; #pragma unroll
;                     for (int j = 0; j < 4; ++j) { const int r = 4 * g4 + j; S[i][r] = d[j] * S[i][r] + AGG[(size_t)((it2 * 8 + wave) * 2 + i) * 1024 + r * 64 + lane]; } } }
; #pragma unroll
;         for (int i = 0; i < 2; ++i)
; #pragma unroll
;             for (int g4 = 0; g4 < 4; ++g4) { u32x2 w; w.x = pk2(S[i][4 * g4], S[i][4 * g4 + 1]); w.y = pk2(S[i][4 * g4 + 2], S[i][4 * g4 + 3]);
;                 *(LAS u32x2*)(lds + HL_ST + ((vb0 + i) * 32 + l31) * 272 + (kb * 32 + 8 * g4 + 4 * lh) * 2) = w; }
;         for (int e = tid; e < 32 * 16; e += NTHR) { const int t = e >> 4, c = e & 15; *(LAS unsigned*)(lds + HL_PP + t * 144 + 64 + c * 4) = 0u; }
;     }
;     float c0[8], c1[8]; unsigned qw[8], ivw[8]; u32x4 ghw0, ghw1;
;     ...
;     HG_LOADS(0);
.LBB0_838:
	s_or_b64 exec, exec, s[18:19]
	s_ashr_i32 s84, s91, 6
	s_and_b32 s18, s2, 7
	s_ashr_i32 s85, s84, 31
	s_lshl_b32 s33, s18, 21
	s_lshl_b32 s19, s54, 1
	s_lshl_b32 s87, s18, 10
	s_lshl_b64 s[52:53], s[84:85], 13
	s_lshl_b32 s18, s26, 10
	s_and_b32 s86, s19, 0x700
	s_or_b32 s18, s52, s18
	s_add_u32 s20, s18, s55
	v_lshlrev_b32_e32 v36, 1, v32
	s_addc_u32 s21, s53, 0
	s_lshl_b32 s22, s91, 4
	s_and_b32 s74, s22, 0x380
	v_ashrrev_i32_e32 v37, 31, v36
	v_lshl_add_u64 v[76:77], v[36:37], 0, s[74:75]
	v_lshlrev_b32_e32 v249, 1, v76
	v_add_u32_e32 v250, 0x1000, v249
	v_add_u32_e32 v251, 0x2000, v249
	v_add_u32_e32 v252, 0x3000, v249
	s_lshl_b64 s[20:21], s[20:21], 10
	v_lshl_add_u64 v[44:45], v[76:77], 0, s[20:21]
	v_lshlrev_b64 v[44:45], 1, v[44:45]
	v_lshl_add_u64 v[46:47], s[70:71], 0, v[44:45]
	global_load_dword v240, v[46:47], off nt
	v_lshl_add_u64 v[48:49], s[62:63], 0, v[44:45]
	global_load_dword v110, v[48:49], off nt
	v_lshl_add_u64 v[48:49], s[64:65], 0, v[44:45]
	s_mov_b64 s[20:21], 0x800
	v_ashrrev_i32_e32 v38, 3, v38
	s_mov_b32 s19, s53
	v_lshlrev_b32_e32 v43, 4, v32
	v_and_b32_e32 v94, 0x70, v43
	v_lshlrev_b32_e32 v74, 1, v94
	v_and_b32_e32 v60, 64, v108
	v_xor_b32_e32 v59, 1, v108
	v_add_u32_e32 v60, 64, v60
	v_cmp_lt_i32_e32 vcc, v59, v60
	v_lshlrev_b32_e32 v128, 4, v40
	v_readlane_b32 s46, v255, 48
	v_cndmask_b32_e32 v59, v108, v59, vcc
	v_lshlrev_b32_e32 v129, 2, v59
	v_xor_b32_e32 v59, 2, v108
	v_cmp_lt_i32_e32 vcc, v59, v60
	v_readlane_b32 s22, v255, 37
	v_readlane_b32 s24, v255, 38
	v_cndmask_b32_e32 v59, v108, v59, vcc
	v_lshlrev_b32_e32 v130, 2, v59
	v_xor_b32_e32 v59, 4, v108
	v_cmp_lt_i32_e32 vcc, v59, v60
	v_readlane_b32 s26, v255, 39
	v_readlane_b32 s28, v255, 40
	v_cndmask_b32_e32 v59, v108, v59, vcc
	v_readlane_b32 s30, v255, 41
	v_readlane_b32 s34, v255, 42
	v_readlane_b32 s36, v255, 43
	v_readlane_b32 s38, v255, 44
	v_readlane_b32 s40, v255, 45
	v_readlane_b32 s42, v255, 46
	v_readlane_b32 s44, v255, 47
	v_add_u32_e32 v96, s46, v34
	v_readlane_b32 s48, v255, 49
	v_readlane_b32 s50, v255, 50
	v_add_u32_e32 v61, s97, v34
	v_add_u32_e32 v63, s22, v34
	v_add_u32_e32 v64, s24, v34
	v_add_u32_e32 v65, s26, v34
	v_add_u32_e32 v66, s28, v34
	v_add_u32_e32 v67, s30, v34
	v_add_u32_e32 v68, s34, v34
	v_add_u32_e32 v69, s36, v34
	v_add_u32_e32 v70, s38, v34
	v_add_u32_e32 v71, s40, v34
	v_add_u32_e32 v72, s42, v34
	v_add_u32_e32 v73, s44, v34
	v_mul_lo_u32 v102, v96, s72
	v_lshlrev_b32_e32 v131, 2, v59
	v_or_b32_e32 v59, s97, v42
	v_lshlrev_b32_e32 v126, 3, v32
	v_mul_lo_u32 v58, v38, s94
	v_mul_u32_u24_e32 v41, 0x110, v33
	v_add_u32_e32 v58, 0, v58
	v_mad_u32_u24 v59, v59, s3, 0
	v_add_u32_e32 v133, v59, v128
	v_add_u32_e32 v156, v35, v41
	global_load_dword v111, v[48:49], off nt
	global_load_dword v241, v[46:47], off offset:2048 nt
	v_lshl_add_u64 v[46:47], v[44:45], 0, s[20:21]
	v_lshl_add_u64 v[48:49], s[62:63], 0, v[46:47]
	v_lshl_add_u64 v[46:47], s[64:65], 0, v[46:47]
	s_mov_b64 s[20:21], 0x1000
	global_load_dword v112, v[48:49], off nt
	global_load_dword v113, v[46:47], off nt
	v_lshl_add_u64 v[46:47], v[44:45], 0, s[20:21]
	v_lshl_add_u64 v[48:49], s[70:71], 0, v[46:47]
	s_mov_b64 s[20:21], 0x1800
	global_load_dword v242, v[48:49], off nt
	v_lshl_add_u64 v[48:49], s[62:63], 0, v[46:47]
	v_lshl_add_u64 v[46:47], s[64:65], 0, v[46:47]
	global_load_dword v114, v[48:49], off nt
	global_load_dword v115, v[46:47], off nt
	v_lshl_add_u64 v[46:47], v[44:45], 0, s[20:21]
	v_lshl_add_u64 v[48:49], s[70:71], 0, v[46:47]
	s_mov_b64 s[20:21], 0x2000
	global_load_dword v243, v[48:49], off nt
	v_lshl_add_u64 v[48:49], s[62:63], 0, v[46:47]
	v_lshl_add_u64 v[46:47], s[64:65], 0, v[46:47]
	global_load_dword v116, v[48:49], off nt
	global_load_dword v117, v[46:47], off nt
	v_lshl_add_u64 v[46:47], v[44:45], 0, s[20:21]
	v_lshl_add_u64 v[48:49], s[70:71], 0, v[46:47]
	s_mov_b64 s[20:21], 0x2800
	global_load_dword v244, v[48:49], off nt
	v_lshl_add_u64 v[48:49], s[62:63], 0, v[46:47]
	v_lshl_add_u64 v[46:47], s[64:65], 0, v[46:47]
	global_load_dword v118, v[48:49], off nt
	global_load_dword v119, v[46:47], off nt
	v_lshl_add_u64 v[46:47], v[44:45], 0, s[20:21]
	v_lshl_add_u64 v[48:49], s[70:71], 0, v[46:47]
	s_mov_b64 s[20:21], 0x3000
	global_load_dword v245, v[48:49], off nt
	v_lshl_add_u64 v[48:49], s[62:63], 0, v[46:47]
	v_lshl_add_u64 v[46:47], s[64:65], 0, v[46:47]
	global_load_dword v120, v[48:49], off nt
	global_load_dword v121, v[46:47], off nt
	v_lshl_add_u64 v[46:47], v[44:45], 0, s[20:21]
	v_lshl_add_u64 v[48:49], s[70:71], 0, v[46:47]
	s_mov_b64 s[20:21], 0x3800
	v_lshl_add_u64 v[44:45], v[44:45], 0, s[20:21]
	v_readlane_b32 s20, v255, 36
	global_load_dword v246, v[48:49], off nt
	v_lshl_add_u64 v[48:49], s[62:63], 0, v[46:47]
	v_lshl_add_u64 v[46:47], s[64:65], 0, v[46:47]
	global_load_dword v122, v[48:49], off nt
	global_load_dword v123, v[46:47], off nt
	v_lshl_add_u64 v[46:47], s[70:71], 0, v[44:45]
	v_add_u32_e32 v62, s20, v34
	global_load_dword v247, v[46:47], off nt
	v_lshl_add_u64 v[46:47], s[62:63], 0, v[44:45]
	v_lshl_add_u64 v[44:45], s[64:65], 0, v[44:45]
	global_load_dword v124, v[46:47], off nt
	global_load_dword v125, v[44:45], off nt
	v_lshlrev_b32_e32 v47, 2, v32
	v_ashrrev_i32_e32 v39, 31, v38
	v_lshl_add_u64 v[44:45], s[18:19], 0, v[38:39]
	v_lshlrev_b64 v[44:45], 11, v[44:45]
	v_lshl_add_u64 v[44:45], s[66:67], 0, v[44:45]
	s_lshl_b32 s18, s74, 1
	s_mov_b32 s19, s75
	v_lshl_add_u64 v[44:45], v[44:45], 0, s[18:19]
	v_lshl_add_u64 v[44:45], v[44:45], 0, v[74:75]
	global_load_dwordx4 v[48:51], v[44:45], off offset:16 nt
	global_load_dwordx4 v[52:55], v[44:45], off nt
	s_movk_i32 s18, 0x120
; #define lane lane_id()
; template <bool FULL, bool STORE = true>
; __device__ __forceinline__ void hg_item(const Prm& P, LAS unsigned char* lds, int item, int wave) {
;     unsigned char* ws = P.ws; const int lane = lane_id(), tid = wave * 64 + lane;
;     const int b = item >> 6, h = (item >> 3) & 7, seg = item & 7;
;     const int l31 = lane & 31, lh = lane >> 5;
;     const int k2 = lane * 2, tg = wave;
;     const int kb = wave >> 1, vb0 = (wave & 1) * 2;
;     const _Float16* LF = (const _Float16*)P.out; const bf16_t* Q = (const bf16_t*)(ws + WS_Q); const bf16_t* IV = (const bf16_t*)(ws + WS_IV); const bf16_t* GH = (const bf16_t*)(ws + WS_GH);
;     bf16_t* AHG = (bf16_t*)(ws + WS_AHG);
;     float* AGG = (float*)(ws + WS_HGAGG); float* DEC = (float*)(ws + WS_HGDEC);
;     f32x16 S[2];
; #pragma unroll
;     for (int i = 0; i < 2; ++i)
; #pragma unroll
;         for (int r = 0; r < 16; ++r) S[i][r] = 0.f;
;     float sumlog0 = 0.f, sumlog1 = 0.f;
;     if (FULL) {
;         for (int s2 = 0; s2 < seg; ++s2) { const int it2 = item - seg + s2;
; #pragma unroll
;             for (int g4 = 0; g4 < 4; ++g4) { const f32x4 d = *(const f32x4*)(DEC + it2 * 128 + kb * 32 + 8 * g4 + 4 * lh);
; #pragma unroll
;                 for (int i = 0; i < 2; ++i)
; #pragma unroll
;                     for (int j = 0; j < 4; ++j) { const int r = 4 * g4 + j; S[i][r] = d[j] * S[i][r] + AGG[(size_t)((it2 * 8 + wave) * 2 + i) * 1024 + r * 64 + lane]; } } }
; #pragma unroll
;         for (int i = 0; i < 2; ++i)
; #pragma unroll
;             for (int g4 = 0; g4 < 4; ++g4) { u32x2 w; w.x = pk2(S[i][4 * g4], S[i][4 * g4 + 1]); w.y = pk2(S[i][4 * g4 + 2], S[i][4 * g4 + 3]);
;                 *(LAS u32x2*)(lds + HL_ST + ((vb0 + i) * 32 + l31) * 272 + (kb * 32 + 8 * g4 + 4 * lh) * 2) = w; }
;         for (int e = tid; e < 32 * 16; e += NTHR) { const int t = e >> 4, c = e & 15; *(LAS unsigned*)(lds + HL_PP + t * 144 + 64 + c * 4) = 0u; }
;     }
;     float c0[8], c1[8]; unsigned qw[8], ivw[8]; u32x4 ghw0, ghw1;
;     ...
;     HG_LOADS(0);
;     for (int ch = 0; ch < 16; ++ch) {
;         const size_t row0 = (size_t)b * SEQ + seg * 1024 + ch * 64;
;         float ka[8], kc[8], f0[8], f1[8]; float t0 = 0.f, t1 = 0.f;
; #pragma unroll
;         for (int i = 0; i < 8; ++i) { f0[i] = __expf(c0[i]); f1[i] = __expf(c1[i]); ka[i] = 1.0f - f0[i]; kc[i] = 1.0f - f1[i]; t0 += c0[i]; t1 += c1[i]; }
	v_mul_lo_u32 v127, v32, s18
	v_readlane_b32 s18, v255, 32
	s_add_i32 s19, 0, 0x15c00
	s_lshl_b32 s74, s74, 2
	v_or_b32_e32 v45, s18, v42
	s_add_i32 s18, 0, 0x11400
	v_mov_b32_e32 v40, s18
	v_add_u32_e32 v57, s18, v128
	v_readlane_b32 s18, v255, 34
	v_mov_b32_e32 v46, s19
	v_add_u32_e32 v74, s59, v34
	v_readlane_b32 s19, v255, 33
	v_or_b32_e32 v95, s18, v42
	v_or_b32_e32 v221, s97, v42
	v_mul_u32_u24_e32 v222, s72, v221
	v_add_lshl_u32 v223, v34, s18, 1
	v_add3_u32 v222, v222, v223, s73
	v_add_u32_e32 v221, s97, v221
	v_subrev_u32_e32 v221, s18, v221
	s_add_u32 vcc_lo, s82, s74
	v_mad_u32_u24 v40, v45, s72, v40
	v_mad_u32_u24 v45, v45, s3, v46
	v_lshl_add_u32 v46, v42, 2, s19
	v_readlane_b32 s19, v255, 29
	v_cmp_lt_i32_e64 s[46:47], v221, v96
	v_add_u32_e32 v96, s48, v34
	v_add_u32_e32 v34, s50, v34
	v_mul_lo_u32 v104, v74, s94
	v_lshlrev_b32_e32 v74, 2, v94
	s_addc_u32 vcc_hi, s83, 0
	v_or_b32_e32 v44, s59, v42
	v_or_b32_e32 v56, s19, v42
	v_mad_u32_u24 v60, v95, s3, 0
	v_lshl_add_u32 v42, v95, 1, s73
	v_cmp_lt_i32_e64 s[18:19], v221, v61
	v_cmp_lt_i32_e64 s[20:21], v221, v62
	v_cmp_lt_i32_e64 s[22:23], v221, v63
	v_cmp_lt_i32_e64 s[24:25], v221, v64
	v_cmp_lt_i32_e64 s[26:27], v221, v65
	v_cmp_lt_i32_e64 s[28:29], v221, v66
	v_cmp_lt_i32_e64 s[30:31], v221, v67
	v_cmp_lt_i32_e64 s[34:35], v221, v68
	v_cmp_lt_i32_e64 s[36:37], v221, v69
	v_cmp_lt_i32_e64 s[38:39], v221, v70
	v_cmp_lt_i32_e64 s[40:41], v221, v71
	v_cmp_lt_i32_e64 s[42:43], v221, v72
	v_cmp_lt_i32_e64 s[44:45], v221, v73
	v_cmp_lt_i32_e64 s[48:49], v221, v96
	v_cmp_lt_i32_e64 s[50:51], v221, v34
	v_lshl_add_u64 v[94:95], vcc, 0, v[74:75]
	s_lshl_b64 vcc, s[84:85], 24
	s_or_b32 vcc_lo, vcc_lo, s33
	v_readlane_b32 s33, v255, 55
	s_add_u32 s33, s33, s52
	s_addc_u32 s53, s90, s53
	v_lshlrev_b64 v[38:39], 11, v[38:39]
	v_and_b32_e32 v32, 7, v32
	s_add_u32 s52, s33, s87
	v_lshl_add_u64 v[38:39], vcc, 0, v[38:39]
	v_lshlrev_b32_e32 v32, 5, v32
	s_addc_u32 s53, s53, 0
	s_or_b32 s33, vcc_lo, s86
	v_mul_lo_u32 v43, v44, s72
	v_mul_lo_u32 v44, v44, s3
	v_mul_lo_u32 v56, v56, s72
	v_mul_lo_u32 v105, v34, s72
	v_mul_u32_u24_e32 v34, 0x90, v33
	v_or3_b32 v38, v38, s86, v32
	v_mov_b32_e32 v32, s33
	v_mov_b32_e32 v33, vcc_hi
	v_add_u32_e32 v43, s73, v43
	v_add_u32_e32 v44, 0, v44
	v_add_u32_e32 v56, 0, v56
	v_mul_lo_u32 v61, v61, s72
	v_mul_lo_u32 v62, v62, s72
	v_mul_lo_u32 v63, v63, s72
	v_mul_lo_u32 v64, v64, s72
	v_mul_lo_u32 v65, v65, s72
	v_mul_lo_u32 v66, v66, s72
	v_mul_lo_u32 v67, v67, s72
	v_mul_lo_u32 v68, v68, s72
	v_mul_lo_u32 v69, v69, s72
	v_mul_lo_u32 v70, v70, s72
	v_mul_lo_u32 v71, v71, s72
	v_mul_lo_u32 v72, v72, s72
	v_mul_lo_u32 v73, v73, s72
	v_mul_lo_u32 v103, v96, s72
	v_lshl_add_u64 v[32:33], v[36:37], 1, v[32:33]
	v_readlane_b32 s33, v255, 51
	v_mov_b32_e32 v253, v38
	v_lshl_add_u64 v[96:97], s[92:93], 0, v[38:39]
	s_lshl_b64 s[84:85], s[52:53], 10
	v_lshl_add_u64 v[98:99], s[78:79], 0, v[32:33]
	v_lshl_add_u64 v[100:101], s[80:81], 0, v[32:33]
	s_mov_b64 s[86:87], 0
	v_add_u32_e32 v132, s33, v47
	v_add_u32_e32 v134, v60, v128
	v_add_u32_e32 v135, v42, v61
	v_add_u32_e32 v136, v42, v62
	v_add_u32_e32 v137, v42, v63
	v_add_u32_e32 v138, v42, v64
	v_add_u32_e32 v139, v42, v65
	v_add_u32_e32 v140, v42, v66
	v_add_u32_e32 v141, v42, v67
	v_add_u32_e32 v142, v42, v68
	v_add_u32_e32 v143, v42, v69
	v_add_u32_e32 v144, v42, v70
	v_add_u32_e32 v145, v42, v71
	v_add_u32_e32 v146, v42, v72
	v_add_u32_e32 v147, v42, v73
	v_add_u32_e32 v148, v42, v102
	v_add_u32_e32 v149, v42, v103
	v_add_u32_e32 v150, v42, v105
	v_add_u32_e32 v151, v44, v128
	v_add_u32_e32 v152, v45, v128
	v_add_u32_e32 v153, v46, v104
	v_add_u32_e32 v154, v56, v128
	v_add_u32_e32 v155, v57, v34
	v_add_u32_e32 v157, v58, v74
	v_add_u32_e32 v158, v43, v128
	v_add_u32_e32 v159, v40, v128
	global_load_dwordx4 v[224:227], v[94:95], off offset:48
	global_load_dwordx4 v[228:231], v[94:95], off offset:32
	global_load_dwordx4 v[232:235], v[94:95], off offset:16
	global_load_dwordx4 v[236:239], v[94:95], off
	s_waitcnt vmcnt(8)
	v_cvt_f32_f16_e32 v78, v240
	v_cvt_f32_f16_sdwa v79, v240 dst_sel:DWORD dst_unused:UNUSED_PAD src0_sel:WORD_1
	v_cvt_f32_f16_e32 v80, v241
	v_cvt_f32_f16_sdwa v81, v241 dst_sel:DWORD dst_unused:UNUSED_PAD src0_sel:WORD_1
	v_cvt_f32_f16_e32 v82, v242
	v_cvt_f32_f16_sdwa v83, v242 dst_sel:DWORD dst_unused:UNUSED_PAD src0_sel:WORD_1
	v_cvt_f32_f16_e32 v84, v243
	v_cvt_f32_f16_sdwa v85, v243 dst_sel:DWORD dst_unused:UNUSED_PAD src0_sel:WORD_1
	v_cvt_f32_f16_e32 v86, v244
	v_cvt_f32_f16_sdwa v87, v244 dst_sel:DWORD dst_unused:UNUSED_PAD src0_sel:WORD_1
	v_cvt_f32_f16_e32 v88, v245
	v_cvt_f32_f16_sdwa v89, v245 dst_sel:DWORD dst_unused:UNUSED_PAD src0_sel:WORD_1
	v_cvt_f32_f16_e32 v90, v246
	v_cvt_f32_f16_sdwa v91, v246 dst_sel:DWORD dst_unused:UNUSED_PAD src0_sel:WORD_1
	v_cvt_f32_f16_e32 v92, v247
	v_cvt_f32_f16_sdwa v93, v247 dst_sel:DWORD dst_unused:UNUSED_PAD src0_sel:WORD_1
	s_nop 0
	v_pk_add_f32 v[32:33], v[78:79], 0 op_sel_hi:[1,0]
	v_pk_add_f32 v[32:33], v[32:33], v[80:81]
	v_pk_add_f32 v[32:33], v[32:33], v[82:83]
	v_pk_add_f32 v[32:33], v[32:33], v[84:85]
	v_pk_add_f32 v[32:33], v[32:33], v[86:87]
	v_pk_add_f32 v[32:33], v[32:33], v[88:89]
	v_pk_add_f32 v[32:33], v[32:33], v[90:91]
	v_pk_add_f32 v[32:33], v[32:33], v[92:93]
	v_add_u32_e32 v36, s60, v126
	ds_write_b64 v36, v[32:33]
	s_waitcnt lgkmcnt(0)
	s_barrier
	s_branch .LBB0_840
; #define LAS __attribute__((address_space(3)))
; template <bool FULL, bool STORE = true>
; __device__ __forceinline__ void hg_item(const Prm& P, LAS unsigned char* lds, int item, int wave) {
;     ...
;         for (int i = 0; i < 8; ++i) { f0[i] = __expf(c0[i]); f1[i] = __expf(c1[i]); ka[i] = 1.0f - f0[i]; kc[i] = 1.0f - f1[i]; t0 += c0[i]; t1 += c1[i]; }
;         *(LAS f32x2*)(lds + HL_TOT + (tg * 128 + k2) * 4) = (f32x2){t0, t1};
;         __syncthreads();
;     ...
;             { const int tb = wave >> 2, vb = wave & 3; f32x16 o;
; #pragma unroll
;                 for (int r = 0; r < 16; ++r) o[r] = 0.f;
; #pragma unroll
;                 for (int ks = 0; ks < 4; ++ks) { if (ks < 2 || tb) { const bf16x8 a = *(const LAS bf16x8*)(lds + HL_PP + (tb * 32 + l31) * 144 + ks * 32 + lh * 16), bb = *(const LAS bf16x8*)(lds + HL_IVT + (vb * 32 + l31) * 144 + ks * 32 + lh * 16);
;                         o = __builtin_amdgcn_mfma_f32_32x32x16_bf16(a, bb, o, 0, 0, 0); } }
; #pragma unroll
;                 for (int ks = 0; ks < 8; ++ks) { const bf16x8 a = *(const LAS bf16x8*)(lds + HL_QD + (tb * 32 + l31) * 272 + ks * 32 + lh * 16), bb = *(const LAS bf16x8*)(lds + HL_ST + (vb * 32 + l31) * 272 + ks * 32 + lh * 16);
;                     o = __builtin_amdgcn_mfma_f32_32x32x16_bf16(a, bb, o, 0, 0, 0); }
; #pragma unroll
;                 for (int r = 0; r < 16; ++r) { const int t = tb * 32 + (r & 3) + 8 * (r >> 2) + 4 * lh; *(LAS float*)(lds + HL_OS + t * 528 + (vb * 32 + l31) * 4) = o[r]; }
;             }
;         }
; #pragma unroll
;         for (int g4 = 0; g4 < 4; ++g4) { const f32x4 d = *(const LAS f32x4*)(lds + HL_DC + (kb * 32 + 8 * g4 + 4 * lh) * 4);
; #pragma unroll
;             for (int i = 0; i < 2; ++i)
; #pragma unroll
;                 for (int j = 0; j < 4; ++j) S[i][4 * g4 + j] *= d[j]; }
; #pragma unroll
;         for (int ks = 0; ks < 4; ++ks) { const bf16x8 a = *(const LAS bf16x8*)(lds + HL_KDT + (kb * 32 + l31) * 144 + ks * 32 + lh * 16);
; #pragma unroll
;             for (int i = 0; i < 2; ++i) { const bf16x8 bb = *(const LAS bf16x8*)(lds + HL_IVT + ((vb0 + i) * 32 + l31) * 144 + ks * 32 + lh * 16); S[i] = __builtin_amdgcn_mfma_f32_32x32x16_bf16(a, bb, S[i], 0, 0, 0); } }
.LBB0_839:
	s_mov_b32 s33, 0x800000
	s_add_u32 s86, s86, 0x20000
	s_addc_u32 s87, s87, 0
	v_lshlrev_b32_e32 v104, 16, v52
	v_and_b32_e32 v105, 0xffff0000, v52
	v_lshlrev_b32_e32 v52, 16, v53
	v_and_b32_e32 v53, 0xffff0000, v53
	s_add_u32 s84, s84, 0x10000
	s_addc_u32 s85, s85, 0
	s_cmp_lg_u32 s86, 0x200000
	s_waitcnt lgkmcnt(6)
	v_mfma_f32_32x32x16_bf16 v[32:47], v[172:175], v[176:179], v[32:47]
	ds_read_b128 v[172:175], v151 offset:34944
	ds_read_b128 v[176:179], v152 offset:128
	s_waitcnt lgkmcnt(6)
	v_mfma_f32_32x32x16_bf16 v[32:47], v[180:183], v[184:187], v[32:47]
	ds_read_b128 v[180:183], v151 offset:34976
	ds_read_b128 v[184:187], v152 offset:160
	s_waitcnt lgkmcnt(6)
	v_mfma_f32_32x32x16_bf16 v[32:47], v[188:191], v[192:195], v[32:47]
	ds_read_b128 v[188:191], v151 offset:35008
	ds_read_b128 v[192:195], v152 offset:192
	s_waitcnt lgkmcnt(6)
	v_mfma_f32_32x32x16_bf16 v[32:47], v[196:199], v[200:203], v[32:47]
	ds_read_b128 v[196:199], v151 offset:35040
	ds_read_b128 v[200:203], v152 offset:224
	s_waitcnt lgkmcnt(6)
	v_mfma_f32_32x32x16_bf16 v[32:47], v[172:175], v[176:179], v[32:47]
	s_waitcnt lgkmcnt(4)
	v_mfma_f32_32x32x16_bf16 v[32:47], v[180:183], v[184:187], v[32:47]
	s_waitcnt lgkmcnt(2)
	v_mfma_f32_32x32x16_bf16 v[32:47], v[188:191], v[192:195], v[32:47]
	s_waitcnt lgkmcnt(0)
	v_mfma_f32_32x32x16_bf16 v[32:47], v[196:199], v[200:203], v[32:47]
	s_nop 11
	ds_write2_b32 v153, v32, v33 offset1:132
	v_add_u32_e32 v32, 0x400, v153
	ds_write2_b32 v32, v34, v35 offset0:8 offset1:140
	v_add_u32_e32 v32, 0x1000, v153
	ds_write2_b32 v32, v36, v37 offset0:32 offset1:164
	v_add_u32_e32 v32, 0x1400, v153
	ds_write2_b32 v32, v38, v39 offset0:40 offset1:172
	v_add_u32_e32 v32, 0x2000, v153
	ds_write2_b32 v32, v40, v41 offset0:64 offset1:196
	v_add_u32_e32 v32, 0x2400, v153
	ds_write2_b32 v32, v42, v43 offset0:72 offset1:204
	v_add_u32_e32 v32, 0x3000, v153
	ds_write2_b32 v32, v44, v45 offset0:96 offset1:228
	v_add_u32_e32 v32, 0x3400, v153
	ds_write2_b32 v32, v46, v47 offset0:104 offset1:236
	v_add_u32_e32 v220, s96, v128
	ds_read_b128 v[32:35], v220
	ds_read_b128 v[36:39], v220 offset:32
	ds_read_b128 v[40:43], v220 offset:64
	ds_read_b128 v[44:47], v220 offset:96
	ds_read_b128 v[172:175], v154 offset:52224
	ds_read_b128 v[188:191], v155
	ds_read_b128 v[204:207], v155 offset:4608
	ds_read_b128 v[176:179], v154 offset:52256
	ds_read_b128 v[192:195], v155 offset:32
	ds_read_b128 v[208:211], v155 offset:4640
	s_waitcnt lgkmcnt(9)
	v_pk_mul_f32 v[0:1], v[0:1], v[32:33]
	v_pk_mul_f32 v[2:3], v[2:3], v[34:35]
	v_pk_mul_f32 v[16:17], v[16:17], v[32:33]
	v_pk_mul_f32 v[18:19], v[18:19], v[34:35]
	s_waitcnt lgkmcnt(8)
	v_pk_mul_f32 v[4:5], v[4:5], v[36:37]
	v_pk_mul_f32 v[6:7], v[6:7], v[38:39]
	v_pk_mul_f32 v[20:21], v[20:21], v[36:37]
	v_pk_mul_f32 v[22:23], v[22:23], v[38:39]
	s_waitcnt lgkmcnt(7)
	v_pk_mul_f32 v[8:9], v[8:9], v[40:41]
	v_pk_mul_f32 v[10:11], v[10:11], v[42:43]
	v_pk_mul_f32 v[24:25], v[24:25], v[40:41]
	v_pk_mul_f32 v[26:27], v[26:27], v[42:43]
	s_waitcnt lgkmcnt(6)
	v_pk_mul_f32 v[12:13], v[12:13], v[44:45]
	v_pk_mul_f32 v[14:15], v[14:15], v[46:47]
	v_pk_mul_f32 v[28:29], v[28:29], v[44:45]
	v_pk_mul_f32 v[30:31], v[30:31], v[46:47]
	ds_read_b128 v[180:183], v154 offset:52288
	ds_read_b128 v[196:199], v155 offset:64
	ds_read_b128 v[212:215], v155 offset:4672
	ds_read_b128 v[184:187], v154 offset:52320
	ds_read_b128 v[200:203], v155 offset:96
	ds_read_b128 v[216:219], v155 offset:4704
	s_waitcnt lgkmcnt(10)
	v_mfma_f32_32x32x16_bf16 v[0:15], v[172:175], v[188:191], v[0:15]
	s_waitcnt lgkmcnt(9)
	v_mfma_f32_32x32x16_bf16 v[16:31], v[172:175], v[204:207], v[16:31]
	s_waitcnt lgkmcnt(7)
	v_mfma_f32_32x32x16_bf16 v[0:15], v[176:179], v[192:195], v[0:15]
	s_waitcnt lgkmcnt(6)
	v_mfma_f32_32x32x16_bf16 v[16:31], v[176:179], v[208:211], v[16:31]
	s_waitcnt lgkmcnt(4)
	v_mfma_f32_32x32x16_bf16 v[0:15], v[180:183], v[196:199], v[0:15]
	s_waitcnt lgkmcnt(3)
	v_mfma_f32_32x32x16_bf16 v[16:31], v[180:183], v[212:215], v[16:31]
	s_waitcnt lgkmcnt(1)
	v_mfma_f32_32x32x16_bf16 v[0:15], v[184:187], v[200:203], v[0:15]
	s_waitcnt vmcnt(18)
	v_cvt_f32_f16_e32 v78, v240
	v_cvt_f32_f16_sdwa v79, v240 dst_sel:DWORD dst_unused:UNUSED_PAD src0_sel:WORD_1
	v_cvt_f32_f16_e32 v80, v241
	v_cvt_f32_f16_sdwa v81, v241 dst_sel:DWORD dst_unused:UNUSED_PAD src0_sel:WORD_1
	v_cvt_f32_f16_e32 v82, v242
	v_cvt_f32_f16_sdwa v83, v242 dst_sel:DWORD dst_unused:UNUSED_PAD src0_sel:WORD_1
	v_cvt_f32_f16_e32 v84, v243
	v_cvt_f32_f16_sdwa v85, v243 dst_sel:DWORD dst_unused:UNUSED_PAD src0_sel:WORD_1
	v_cvt_f32_f16_e32 v86, v244
	v_cvt_f32_f16_sdwa v87, v244 dst_sel:DWORD dst_unused:UNUSED_PAD src0_sel:WORD_1
	v_cvt_f32_f16_e32 v88, v245
	v_cvt_f32_f16_sdwa v89, v245 dst_sel:DWORD dst_unused:UNUSED_PAD src0_sel:WORD_1
	v_cvt_f32_f16_e32 v90, v246
	v_cvt_f32_f16_sdwa v91, v246 dst_sel:DWORD dst_unused:UNUSED_PAD src0_sel:WORD_1
	v_cvt_f32_f16_e32 v92, v247
	v_cvt_f32_f16_sdwa v93, v247 dst_sel:DWORD dst_unused:UNUSED_PAD src0_sel:WORD_1
	s_nop 0
	v_pk_add_f32 v[32:33], v[78:79], 0 op_sel_hi:[1,0]
	v_pk_add_f32 v[32:33], v[32:33], v[80:81]
	v_pk_add_f32 v[32:33], v[32:33], v[82:83]
	v_pk_add_f32 v[32:33], v[32:33], v[84:85]
	v_pk_add_f32 v[32:33], v[32:33], v[86:87]
	v_pk_add_f32 v[32:33], v[32:33], v[88:89]
	v_pk_add_f32 v[32:33], v[32:33], v[90:91]
	v_pk_add_f32 v[32:33], v[32:33], v[92:93]
	v_add_u32_e32 v36, s60, v126
	ds_write_b64 v36, v[32:33]
	s_waitcnt lgkmcnt(0)
	s_barrier
; #define LAS __attribute__((address_space(3)))
; __device__ __forceinline__ unsigned pk2(float lo, float hi) { typedef float f2v __attribute__((ext_vector_type(2))); typedef __bf16 b2v __attribute__((ext_vector_type(2))); const f2v v = {lo, hi}; const b2v b = __builtin_convertvector(v, b2v); return __builtin_bit_cast(unsigned, b); }
; __device__ __forceinline__ u32x4 pack8(const float (&f)[8]) { u32x4 w; w.x = pk2(f[0], f[1]); w.y = pk2(f[2], f[3]); w.z = pk2(f[4], f[5]); w.w = pk2(f[6], f[7]); return w; }
; template <bool FULL, bool STORE = true>
; __device__ __forceinline__ void hg_item(const Prm& P, LAS unsigned char* lds, int item, int wave) {
;     ...
;         if (FULL) {
;             __syncthreads();
; #pragma unroll
;             for (int i = 0; i < 2; ++i)
; #pragma unroll
;                 for (int g4 = 0; g4 < 4; ++g4) { u32x2 w; w.x = pk2(S[i][4 * g4], S[i][4 * g4 + 1]); w.y = pk2(S[i][4 * g4 + 2], S[i][4 * g4 + 3]);
;                     *(LAS u32x2*)(lds + HL_ST + ((vb0 + i) * 32 + l31) * 272 + (kb * 32 + 8 * g4 + 4 * lh) * 2) = w; }
;             { const int t = tid >> 3, vs = (tid & 7) * 16; float o[16]; float ss = 0.f;
; #pragma unroll
;                 for (int q4 = 0; q4 < 4; ++q4) { const f32x4 x4 = *(const LAS f32x4*)(lds + HL_OS + t * 528 + (vs + 4 * q4) * 4);
; #pragma unroll
;                     for (int j = 0; j < 4; ++j) { o[4 * q4 + j] = x4[j]; ss += x4[j] * x4[j]; } }
;                 ss += __shfl_xor(ss, 1); ss += __shfl_xor(ss, 2); ss += __shfl_xor(ss, 4);
;                 const float r = rsqrtf(ss * (1.0f / 128.0f) + EPS);
;                 const size_t oo = (row0 + t) * 1024 + h * 128 + vs; const float* gn = P.in[I_HGNG] + h * 128 + vs;
;                 float g0[8], g1[8]; unpack8(gcur0, g0); unpack8(gcur1, g1);
;                 float w0[8], w1[8];
; #pragma unroll
;                 for (int j = 0; j < 8; ++j) { w0[j] = o[j] * r * gn[j] * g0[j]; w1[j] = o[8 + j] * r * gn[8 + j] * g1[j]; }
;                 if (STORE) { *(u32x4*)(AHG + oo) = pack8(w0); *(u32x4*)(AHG + oo + 8) = pack8(w1); }
;             }
	v_mfma_f32_32x32x16_bf16 v[16:31], v[184:187], v[216:219], v[16:31]
	s_nop 8
	v_cvt_pk_bf16_f32 v32, v0, v1
	v_cvt_pk_bf16_f32 v33, v2, v3
	v_cvt_pk_bf16_f32 v34, v4, v5
	v_cvt_pk_bf16_f32 v35, v6, v7
	ds_write2_b64 v156, v[32:33], v[34:35] offset1:2
	v_cvt_pk_bf16_f32 v32, v8, v9
	v_cvt_pk_bf16_f32 v33, v10, v11
	v_cvt_pk_bf16_f32 v34, v12, v13
	v_cvt_pk_bf16_f32 v35, v14, v15
	ds_write2_b64 v156, v[32:33], v[34:35] offset0:4 offset1:6
	v_cvt_pk_bf16_f32 v32, v16, v17
	v_cvt_pk_bf16_f32 v33, v18, v19
	v_cvt_pk_bf16_f32 v34, v20, v21
	v_cvt_pk_bf16_f32 v35, v22, v23
	v_add_u32_e32 v36, 0x2000, v156
	ds_write2_b64 v36, v[32:33], v[34:35] offset0:64 offset1:66
	v_cvt_pk_bf16_f32 v32, v24, v25
	v_cvt_pk_bf16_f32 v33, v26, v27
	v_cvt_pk_bf16_f32 v34, v28, v29
	v_cvt_pk_bf16_f32 v35, v30, v31
	ds_write2_b64 v36, v[32:33], v[34:35] offset0:68 offset1:70
	ds_read_b128 v[66:69], v157
	ds_read_b128 v[36:39], v157 offset:16
	ds_read_b128 v[44:47], v157 offset:32
	ds_read_b128 v[32:35], v157 offset:48
	s_waitcnt lgkmcnt(3)
	v_mul_f32_e32 v64, v67, v67
	v_fmac_f32_e32 v64, v66, v66
	v_fmac_f32_e32 v64, v68, v68
	v_fmac_f32_e32 v64, v69, v69
	s_waitcnt lgkmcnt(2)
	v_fmac_f32_e32 v64, v36, v36
	v_fmac_f32_e32 v64, v37, v37
	v_fmac_f32_e32 v64, v38, v38
	v_fmac_f32_e32 v64, v39, v39
	s_waitcnt lgkmcnt(1)
	v_pk_mul_f32 v[42:43], v[44:45], v[44:45]
	v_pk_mul_f32 v[40:41], v[46:47], v[46:47]
	v_add_f32_e32 v42, v42, v64
	v_add_f32_e32 v42, v43, v42
	v_add_f32_e32 v40, v40, v42
	v_add_f32_e32 v64, v41, v40
	s_waitcnt lgkmcnt(0)
	s_barrier
	v_pk_mul_f32 v[42:43], v[32:33], v[32:33]
	v_pk_mul_f32 v[40:41], v[34:35], v[34:35]
	v_add_f32_e32 v42, v42, v64
	v_add_f32_e32 v42, v43, v42
	v_add_f32_e32 v40, v40, v42
	v_add_f32_e32 v40, v41, v40
	s_nop 1
	v_add_f32_dpp v40, v40, v40 quad_perm:[1,0,3,2] row_mask:0xf bank_mask:0xf
	s_nop 1
	v_add_f32_dpp v40, v40, v40 quad_perm:[2,3,0,1] row_mask:0xf bank_mask:0xf
	s_nop 1
	v_add_f32_dpp v40, v40, v40 row_half_mirror row_mask:0xf bank_mask:0xf
	v_fmamk_f32 v40, v40, 0x3c000000, v109
	v_cmp_gt_f32_e32 vcc, s33, v40
	v_mul_f32_e32 v41, 0x4b800000, v40
	s_mov_b32 s33, 0x7400000
	v_cndmask_b32_e32 v40, v40, v41, vcc
	v_rsq_f32_e32 v40, v40
	s_nop 0
	v_mul_f32_e32 v41, 0x45800000, v40
	v_cndmask_b32_e32 v74, v40, v41, vcc
	v_pk_mul_f32 v[106:107], v[66:67], v[74:75] op_sel_hi:[1,0]
	v_pk_mul_f32 v[46:47], v[46:47], v[74:75] op_sel_hi:[1,0]
	v_pk_mul_f32 v[36:37], v[36:37], v[74:75] op_sel_hi:[1,0]
	v_pk_mul_f32 v[32:33], v[32:33], v[74:75] op_sel_hi:[1,0]
	v_pk_mul_f32 v[44:45], v[44:45], v[74:75] op_sel_hi:[1,0]
	v_pk_mul_f32 v[38:39], v[38:39], v[74:75] op_sel_hi:[1,0]
	v_pk_mul_f32 v[34:35], v[34:35], v[74:75] op_sel_hi:[1,0]
	s_waitcnt vmcnt(0)
	v_pk_mul_f32 v[32:33], v[224:225], v[32:33]
	v_pk_mul_f32 v[46:47], v[230:231], v[46:47]
	v_pk_mul_f32 v[36:37], v[232:233], v[36:37]
	v_pk_mul_f32 v[106:107], v[236:237], v[106:107]
	v_pk_mul_f32 v[44:45], v[228:229], v[44:45]
	v_pk_mul_f32 v[104:105], v[106:107], v[104:105]
	v_lshlrev_b32_e32 v106, 16, v48
	v_and_b32_e32 v107, 0xffff0000, v48
	v_lshlrev_b32_e32 v48, 16, v49
	v_and_b32_e32 v49, 0xffff0000, v49
	v_pk_mul_f32 v[46:47], v[46:47], v[48:49]
	v_lshlrev_b32_e32 v48, 16, v54
	v_and_b32_e32 v49, 0xffff0000, v54
	v_pk_mul_f32 v[36:37], v[36:37], v[48:49]
	v_lshlrev_b32_e32 v48, 16, v50
	v_and_b32_e32 v49, 0xffff0000, v50
	v_pk_mul_f32 v[64:65], v[68:69], v[74:75] op_sel_hi:[1,0]
	v_pk_mul_f32 v[40:41], v[32:33], v[48:49]
	v_lshlrev_b32_e32 v32, 16, v55
	v_and_b32_e32 v33, 0xffff0000, v55
	v_pk_mul_f32 v[38:39], v[234:235], v[38:39]
	v_pk_mul_f32 v[64:65], v[238:239], v[64:65]
	v_pk_mul_f32 v[38:39], v[38:39], v[32:33]
	v_lshlrev_b32_e32 v32, 16, v51
	v_and_b32_e32 v33, 0xffff0000, v51
	v_pk_mul_f32 v[34:35], v[226:227], v[34:35]
	v_pk_mul_f32 v[52:53], v[64:65], v[52:53]
	v_pk_mul_f32 v[42:43], v[34:35], v[32:33]
	v_cvt_pk_bf16_f32 v34, v36, v37
	v_add_co_u32_e32 v36, vcc, s33, v102
	v_pk_mul_f32 v[44:45], v[44:45], v[106:107]
	v_cvt_pk_bf16_f32 v32, v104, v105
	v_cvt_pk_bf16_f32 v33, v52, v53
	v_cvt_pk_bf16_f32 v35, v38, v39
	v_addc_co_u32_e32 v37, vcc, 0, v103, vcc
	v_mov_b64_e32 v[52:53], v[56:57]
	v_mov_b64_e32 v[48:49], v[60:61]
	global_store_dwordx4 v[36:37], v[32:35], off
	v_mov_b64_e32 v[54:55], v[58:59]
	v_mov_b64_e32 v[50:51], v[62:63]
	v_cvt_pk_bf16_f32 v32, v44, v45
	v_cvt_pk_bf16_f32 v33, v46, v47
	v_cvt_pk_bf16_f32 v34, v40, v41
	v_cvt_pk_bf16_f32 v35, v42, v43
	global_store_dwordx4 v[36:37], v[32:35], off offset:16
	s_cbranch_scc0 .LBB0_821
; #define LAS __attribute__((address_space(3)))
; __device__ __forceinline__ unsigned pk2(float lo, float hi) { typedef float f2v __attribute__((ext_vector_type(2))); typedef __bf16 b2v __attribute__((ext_vector_type(2))); const f2v v = {lo, hi}; const b2v b = __builtin_convertvector(v, b2v); return __builtin_bit_cast(unsigned, b); }
; template <bool FULL, bool STORE = true>
; __device__ __forceinline__ void hg_item(const Prm& P, LAS unsigned char* lds, int item, int wave) {
;     ...
;         float off0 = 0.f, off1 = 0.f, bm0 = 0.f, bm1 = 0.f, bl0 = 0.f, bl1 = 0.f;
; #pragma unroll
;         for (int g8 = 0; g8 < 8; ++g8) { const f32x2 t2 = *(const LAS f32x2*)(lds + HL_TOT + (g8 * 128 + k2) * 4); if (g8 < tg) { off0 += t2.x; off1 += t2.y; } if (g8 < 4) { bm0 += t2.x; bm1 += t2.y; } bl0 += t2.x; bl1 += t2.y; }
;         {
;             float kd0[8], kd1[8], iv0[8], iv1[8];
;             float e0 = __expf(off0 + c0[0] - bm0), e1 = __expf(off1 + c1[0] - bm1);
;             const float ebm0 = __expf(bm0), ebm1 = __expf(bm1), ebl0 = __expf(bl0 - bm0), ebl1 = __expf(bl1 - bm1);
; #pragma unroll
;             for (int i = 0; i < 8; ++i) { if (i) { e0 *= f0[i]; e1 *= f1[i]; }
;                 const float r0 = __builtin_amdgcn_rcpf(e0), r1 = __builtin_amdgcn_rcpf(e1);
;                 kd0[i] = ka[i] * r0 * ebl0; kd1[i] = kc[i] * r1 * ebl1; iv0[i] = bflo(ivw[i]); iv1[i] = bfhi(ivw[i]);
;                 if (FULL) { const float qa = bflo(qw[i]), qc = bfhi(qw[i]); const int t = tg * 8 + i;
;                     *(LAS unsigned*)(lds + HL_QM + t * 272 + k2 * 2) = pk2(qa * e0, qc * e1);
;                     *(LAS unsigned*)(lds + HL_KM + t * 272 + k2 * 2) = pk2(ka[i] * r0, kc[i] * r1);
;                     *(LAS unsigned*)(lds + HL_QD + t * 272 + k2 * 2) = pk2(qa * e0 * ebm0, qc * e1 * ebm1); } }
.LBB0_840:
	s_nop 0
	v_add_u32_e32 v44, 0, v126
	v_add_u32_e32 v64, 0x20800, v44
	v_mul_f32_e32 v45, 0x3fb8aa3b, v92
	v_mul_f32_e32 v34, 0x3fb8aa3b, v80
	v_exp_f32_e32 v46, v34
	v_mul_f32_e32 v34, 0x3fb8aa3b, v81
	ds_read2st64_b64 v[36:39], v64 offset1:1
	ds_read2st64_b64 v[56:59], v64 offset0:2 offset1:3
	v_exp_f32_e32 v32, v45
	v_exp_f32_e32 v47, v34
	v_mul_f32_e32 v34, 0x3fb8aa3b, v82
	s_waitcnt lgkmcnt(1)
	v_add_f32_e32 v36, 0, v36
	v_cndmask_b32_e64 v60, v36, 0, s[88:89]
	v_add_f32_e32 v37, 0, v37
	v_add_f32_e32 v61, v38, v60
	v_cndmask_b32_e64 v45, v37, 0, s[88:89]
	v_cndmask_b32_e64 v60, v60, v61, s[6:7]
	v_add_f32_e32 v62, v39, v45
	v_add_f32_e32 v36, v36, v38
	v_add_f32_e32 v38, v37, v39
	s_waitcnt lgkmcnt(0)
	v_add_f32_e32 v37, v56, v60
	v_cndmask_b32_e64 v45, v45, v62, s[6:7]
	v_cndmask_b32_e64 v65, v60, v37, s[8:9]
	ds_read2st64_b64 v[60:63], v64 offset0:4 offset1:5
	v_add_f32_e32 v39, v57, v45
	v_cndmask_b32_e64 v45, v45, v39, s[8:9]
	v_add_f32_e32 v37, v36, v56
	v_add_f32_e32 v39, v38, v57
	v_add_f32_e32 v36, v58, v65
	v_add_f32_e32 v38, v59, v45
	v_cndmask_b32_e64 v38, v45, v38, s[4:5]
	v_cndmask_b32_e64 v36, v65, v36, s[4:5]
	ds_read2st64_b64 v[64:67], v64 offset0:6 offset1:7
	s_waitcnt lgkmcnt(1)
	v_add_f32_e32 v45, v60, v36
	v_add_f32_e32 v56, v61, v38
	v_cndmask_b32_e64 v38, v38, v56, s[10:11]
	v_cndmask_b32_e64 v36, v36, v45, s[10:11]
	v_add_f32_e32 v45, v62, v36
	v_add_f32_e32 v56, v63, v38
	v_cndmask_b32_e64 v38, v38, v56, s[12:13]
	v_cndmask_b32_e64 v36, v36, v45, s[12:13]
	s_waitcnt lgkmcnt(0)
	v_add_f32_e32 v45, v64, v36
	v_add_f32_e32 v56, v65, v38
	v_cndmask_b32_e64 v38, v38, v56, s[14:15]
	v_cndmask_b32_e64 v36, v36, v45, s[14:15]
	v_add_f32_e32 v45, v66, v36
	v_add_f32_e32 v56, v67, v38
	v_cndmask_b32_e64 v38, v38, v56, s[16:17]
	v_cndmask_b32_e64 v36, v36, v45, s[16:17]
	v_mov_b32_e32 v56, v78
	v_mov_b32_e32 v57, v58
	v_pk_add_f32 v[56:57], v[56:57], v[36:37]
	v_mov_b32_e32 v58, v79
	v_pk_add_f32 v[36:37], v[56:57], v[60:61] op_sel:[1,0] op_sel_hi:[0,1]
	v_pk_add_f32 v[36:37], v[36:37], v[62:63]
	v_pk_add_f32 v[58:59], v[58:59], v[38:39]
	v_pk_add_f32 v[36:37], v[36:37], v[64:65]
	v_pk_add_f32 v[38:39], v[58:59], v[60:61]
	v_pk_add_f32 v[36:37], v[36:37], v[66:67]
	v_pk_add_f32 v[38:39], v[38:39], v[62:63]
	v_sub_f32_e32 v37, v56, v57
	v_mul_f32_e32 v37, 0x3fb8aa3b, v37
	v_exp_f32_e32 v72, v37
	v_sub_f32_e32 v37, v58, v59
	v_mul_f32_e32 v37, 0x3fb8aa3b, v37
	v_exp_f32_e32 v73, v37
	v_mul_f32_e32 v37, 0x3fb8aa3b, v57
	v_exp_f32_e32 v60, v37
	v_mul_f32_e32 v37, 0x3fb8aa3b, v59
	v_mul_f32_e32 v45, 0x3fb8aa3b, v79
	v_pk_add_f32 v[38:39], v[38:39], v[64:65]
	v_exp_f32_e32 v61, v37
	v_sub_f32_e32 v37, v36, v57
	v_exp_f32_e32 v57, v45
	v_mul_f32_e32 v45, 0x3fb8aa3b, v78
	v_pk_add_f32 v[38:39], v[38:39], v[66:67]
	v_mul_f32_e32 v37, 0x3fb8aa3b, v37
	v_exp_f32_e32 v56, v45
	v_exp_f32_e32 v38, v37
	v_sub_f32_e32 v37, v39, v59
	v_rcp_f32_e32 v58, v72
	v_rcp_f32_e32 v59, v73
	v_pk_add_f32 v[56:57], v[56:57], 1.0 op_sel_hi:[1,0] neg_lo:[1,0] neg_hi:[1,0]
	v_mul_f32_e32 v37, 0x3fb8aa3b, v37
	v_exp_f32_e32 v62, v37
	v_pk_mul_f32 v[56:57], v[56:57], v[58:59]
	v_lshlrev_b32_e32 v58, 16, v111
	v_and_b32_e32 v59, 0xffff0000, v111
	v_pk_mul_f32 v[58:59], v[72:73], v[58:59]
	v_lshlrev_b32_e32 v66, 16, v113
	v_cvt_pk_bf16_f32 v63, v58, v59
	v_pk_mul_f32 v[58:59], v[60:61], v[58:59]
	v_and_b32_e32 v67, 0xffff0000, v113
	v_cvt_pk_bf16_f32 v102, v58, v59
	v_pk_mul_f32 v[58:59], v[46:47], v[72:73]
	v_pk_add_f32 v[46:47], v[46:47], 1.0 op_sel_hi:[1,0] neg_lo:[1,0] neg_hi:[1,0]
	v_rcp_f32_e32 v64, v58
	v_rcp_f32_e32 v65, v59
	v_exp_f32_e32 v68, v34
	v_mul_f32_e32 v34, 0x3fb8aa3b, v83
	v_pk_mul_f32 v[66:67], v[58:59], v[66:67]
	v_pk_mul_f32 v[46:47], v[46:47], v[64:65]
	v_exp_f32_e32 v69, v34
	v_mul_f32_e32 v34, 0x3fb8aa3b, v84
	v_cvt_pk_bf16_f32 v74, v56, v57
	v_mov_b32_e32 v64, v56
	v_mov_b32_e32 v56, v57
	v_mov_b32_e32 v57, v47
	v_cvt_pk_bf16_f32 v72, v66, v67
	v_exp_f32_e32 v70, v34
	v_mul_f32_e32 v34, 0x3fb8aa3b, v85
	v_mov_b32_e32 v65, v46
	v_pk_mul_f32 v[56:57], v[62:63], v[56:57] op_sel_hi:[0,1]
	ds_write2_b32 v132, v63, v72 offset1:68
	v_cvt_pk_bf16_f32 v46, v46, v47
	v_add_u32_e32 v63, 0x4400, v132
	v_exp_f32_e32 v71, v34
	ds_write2_b32 v63, v74, v46 offset1:68
	v_pk_mul_f32 v[46:47], v[60:61], v[66:67]
	v_add_u32_e32 v72, 0x8800, v132
	v_cvt_pk_bf16_f32 v46, v46, v47
	ds_write2_b32 v72, v102, v46 offset1:68
	v_pk_mul_f32 v[46:47], v[68:69], v[58:59]
	v_lshlrev_b32_e32 v66, 16, v115
	v_and_b32_e32 v67, 0xffff0000, v115
	v_pk_mul_f32 v[66:67], v[46:47], v[66:67]
	v_rcp_f32_e32 v58, v46
	v_rcp_f32_e32 v59, v47
	v_cvt_pk_bf16_f32 v102, v66, v67
	v_pk_mul_f32 v[66:67], v[60:61], v[66:67]
	v_pk_mul_f32 v[46:47], v[70:71], v[46:47]
	v_mul_f32_e32 v34, 0x3fb8aa3b, v86
	v_cvt_pk_bf16_f32 v106, v66, v67
	v_rcp_f32_e32 v66, v46
	v_rcp_f32_e32 v67, v47
	v_exp_f32_e32 v42, v34
	v_mul_f32_e32 v34, 0x3fb8aa3b, v87
	v_exp_f32_e32 v43, v34
	v_pk_add_f32 v[68:69], v[68:69], 1.0 op_sel_hi:[1,0] neg_lo:[1,0] neg_hi:[1,0]
	v_pk_add_f32 v[70:71], v[70:71], 1.0 op_sel_hi:[1,0] neg_lo:[1,0] neg_hi:[1,0]
	v_pk_mul_f32 v[58:59], v[68:69], v[58:59]
	v_lshlrev_b32_e32 v68, 16, v117
	v_and_b32_e32 v69, 0xffff0000, v117
	v_pk_mul_f32 v[66:67], v[70:71], v[66:67]
	v_cvt_pk_bf16_f32 v105, v58, v59
	v_mov_b32_e32 v71, v66
	v_pk_mul_f32 v[68:69], v[46:47], v[68:69]
	v_cvt_pk_bf16_f32 v66, v66, v67
	v_mul_f32_e32 v34, 0x3fb8aa3b, v88
	v_mov_b32_e32 v70, v58
	v_mov_b32_e32 v58, v59
	v_mov_b32_e32 v59, v67
	ds_write2_b32 v63, v105, v66 offset0:136 offset1:204
	v_pk_mul_f32 v[66:67], v[60:61], v[68:69]
	v_pk_mul_f32 v[46:47], v[42:43], v[46:47]
	v_exp_f32_e32 v40, v34
; #define LAS __attribute__((address_space(3)))
; __device__ __forceinline__ unsigned pk2(float lo, float hi) { typedef float f2v __attribute__((ext_vector_type(2))); typedef __bf16 b2v __attribute__((ext_vector_type(2))); const f2v v = {lo, hi}; const b2v b = __builtin_convertvector(v, b2v); return __builtin_bit_cast(unsigned, b); }
; __device__ __forceinline__ u32x4 pack8(const float (&f)[8]) { u32x4 w; w.x = pk2(f[0], f[1]); w.y = pk2(f[2], f[3]); w.z = pk2(f[4], f[5]); w.w = pk2(f[6], f[7]); return w; }
; template <bool FULL, bool STORE = true>
; __device__ __forceinline__ void hg_item(const Prm& P, LAS unsigned char* lds, int item, int wave) {
;     ...
;             for (int i = 0; i < 8; ++i) { if (i) { e0 *= f0[i]; e1 *= f1[i]; }
;                 const float r0 = __builtin_amdgcn_rcpf(e0), r1 = __builtin_amdgcn_rcpf(e1);
;                 kd0[i] = ka[i] * r0 * ebl0; kd1[i] = kc[i] * r1 * ebl1; iv0[i] = bflo(ivw[i]); iv1[i] = bfhi(ivw[i]);
;                 if (FULL) { const float qa = bflo(qw[i]), qc = bfhi(qw[i]); const int t = tg * 8 + i;
;                     *(LAS unsigned*)(lds + HL_QM + t * 272 + k2 * 2) = pk2(qa * e0, qc * e1);
;                     *(LAS unsigned*)(lds + HL_KM + t * 272 + k2 * 2) = pk2(ka[i] * r0, kc[i] * r1);
;                     *(LAS unsigned*)(lds + HL_QD + t * 272 + k2 * 2) = pk2(qa * e0 * ebm0, qc * e1 * ebm1); } }
;             *(LAS u32x4*)(lds + HL_KDT + k2 * 144 + tg * 16) = pack8(kd0); *(LAS u32x4*)(lds + HL_KDT + (k2 + 1) * 144 + tg * 16) = pack8(kd1);
;             *(LAS u32x4*)(lds + HL_IVT + k2 * 144 + tg * 16) = pack8(iv0); *(LAS u32x4*)(lds + HL_IVT + (k2 + 1) * 144 + tg * 16) = pack8(iv1);
;             if (tg == 0) { *(LAS f32x2*)(lds + HL_DC + k2 * 4) = (f32x2){__expf(bl0), __expf(bl1)}; sumlog0 += bl0; sumlog1 += bl1; }
;         }
;         const u32x4 gcur0 = ghw0, gcur1 = ghw1;
;         if (ch + 1 < 16) HG_LOADS(ch + 1);
	v_mul_f32_e32 v34, 0x3fb8aa3b, v89
	v_pk_mul_f32 v[58:59], v[62:63], v[58:59] op_sel_hi:[0,1]
	v_cvt_pk_bf16_f32 v63, v66, v67
	v_rcp_f32_e32 v66, v46
	v_rcp_f32_e32 v67, v47
	v_exp_f32_e32 v41, v34
	v_cvt_pk_bf16_f32 v161, v68, v69
	v_lshlrev_b32_e32 v68, 16, v119
	v_and_b32_e32 v69, 0xffff0000, v119
	v_pk_add_f32 v[42:43], v[42:43], 1.0 op_sel_hi:[1,0] neg_lo:[1,0] neg_hi:[1,0]
	ds_write2_b32 v72, v106, v63 offset0:136 offset1:204
	v_pk_mul_f32 v[42:43], v[42:43], v[66:67]
	v_pk_mul_f32 v[66:67], v[46:47], v[68:69]
	v_pk_mul_f32 v[46:47], v[40:41], v[46:47]
	v_cvt_pk_bf16_f32 v63, v66, v67
	v_pk_mul_f32 v[66:67], v[60:61], v[66:67]
	v_lshlrev_b32_e32 v68, 16, v121
	v_cvt_pk_bf16_f32 v106, v66, v67
	v_rcp_f32_e32 v66, v46
	v_rcp_f32_e32 v67, v47
	v_and_b32_e32 v69, 0xffff0000, v121
	v_mul_f32_e32 v34, 0x3fb8aa3b, v90
	v_mul_f32_e32 v35, 0x3fb8aa3b, v91
	v_pk_add_f32 v[40:41], v[40:41], 1.0 op_sel_hi:[1,0] neg_lo:[1,0] neg_hi:[1,0]
	v_pk_mul_f32 v[68:69], v[46:47], v[68:69]
	v_exp_f32_e32 v34, v34
	v_exp_f32_e32 v35, v35
	v_pk_mul_f32 v[40:41], v[40:41], v[66:67]
	v_cvt_pk_bf16_f32 v163, v68, v69
	v_add_u32_e32 v164, 0x400, v132
	v_cvt_pk_bf16_f32 v105, v42, v43
	v_mov_b32_e32 v67, v40
	ds_write2_b32 v164, v63, v163 offset0:16 offset1:84
	v_cvt_pk_bf16_f32 v40, v40, v41
	v_add_u32_e32 v163, 0x4800, v132
	v_mov_b32_e32 v66, v42
	v_mov_b32_e32 v42, v43
	v_mov_b32_e32 v43, v41
	ds_write2_b32 v163, v105, v40 offset0:16 offset1:84
	v_pk_mul_f32 v[40:41], v[60:61], v[68:69]
	v_add_u32_e32 v105, 0x8c00, v132
	v_cvt_pk_bf16_f32 v40, v40, v41
	ds_write2_b32 v105, v106, v40 offset0:16 offset1:84
	v_pk_mul_f32 v[40:41], v[34:35], v[46:47]
	v_mul_f32_e32 v33, 0x3fb8aa3b, v93
	v_rcp_f32_e32 v46, v40
	v_rcp_f32_e32 v47, v41
	v_exp_f32_e32 v33, v33
	v_lshlrev_b32_e32 v68, 16, v123
	v_and_b32_e32 v69, 0xffff0000, v123
	v_pk_add_f32 v[34:35], v[34:35], 1.0 op_sel_hi:[1,0] neg_lo:[1,0] neg_hi:[1,0]
	v_pk_mul_f32 v[42:43], v[62:63], v[42:43] op_sel_hi:[0,1]
	v_pk_mul_f32 v[34:35], v[34:35], v[46:47]
	v_pk_mul_f32 v[46:47], v[40:41], v[68:69]
	v_pk_mul_f32 v[40:41], v[32:33], v[40:41]
	v_cvt_pk_bf16_f32 v166, v46, v47
	v_pk_mul_f32 v[46:47], v[60:61], v[46:47]
	v_pk_add_f32 v[32:33], v[32:33], 1.0 op_sel_hi:[1,0] neg_lo:[1,0] neg_hi:[1,0]
	v_cvt_pk_bf16_f32 v168, v46, v47
	v_rcp_f32_e32 v46, v40
	v_rcp_f32_e32 v47, v41
	v_cvt_pk_bf16_f32 v167, v34, v35
	s_waitcnt vmcnt(2)
	v_lshlrev_b32_e32 v68, 16, v125
	v_and_b32_e32 v69, 0xffff0000, v125
	v_pk_mul_f32 v[32:33], v[32:33], v[46:47]
	v_mov_b32_e32 v46, v34
	v_mov_b32_e32 v34, v35
	v_mov_b32_e32 v35, v33
	v_mov_b32_e32 v47, v32
	v_pk_mul_f32 v[62:63], v[62:63], v[34:35] op_sel_hi:[0,1]
	v_pk_mul_f32 v[34:35], v[40:41], v[68:69]
	v_cvt_pk_bf16_f32 v32, v32, v33
	ds_write2_b32 v163, v167, v32 offset0:152 offset1:220
	v_pk_mul_f32 v[32:33], v[60:61], v[34:35]
	v_pk_mul_f32 v[64:65], v[38:39], v[64:65] op_sel_hi:[0,1]
	v_pk_mul_f32 v[70:71], v[38:39], v[70:71] op_sel_hi:[0,1]
	v_pk_mul_f32 v[66:67], v[38:39], v[66:67] op_sel_hi:[0,1]
	v_pk_mul_f32 v[46:47], v[38:39], v[46:47] op_sel_hi:[0,1]
	v_cvt_pk_bf16_f32 v38, v34, v35
	v_cvt_pk_bf16_f32 v32, v32, v33
	ds_write2_b32 v164, v166, v38 offset0:152 offset1:220
	ds_write2_b32 v105, v168, v32 offset0:152 offset1:220
	v_cvt_pk_bf16_f32 v32, v64, v65
	v_cvt_pk_bf16_f32 v33, v70, v71
	v_cvt_pk_bf16_f32 v34, v66, v67
	v_cvt_pk_bf16_f32 v35, v46, v47
	v_add_u32_e32 v38, s61, v127
	v_lshlrev_b32_e32 v37, 16, v110
	v_lshlrev_b32_e32 v103, 16, v112
	v_lshlrev_b32_e32 v73, 16, v114
	v_lshlrev_b32_e32 v107, 16, v116
	ds_write2_b32 v132, v102, v161 offset0:136 offset1:204
	v_lshlrev_b32_e32 v72, 16, v118
	v_lshlrev_b32_e32 v161, 16, v120
	v_lshlrev_b32_e32 v106, 16, v122
	v_lshlrev_b32_e32 v169, 16, v124
	ds_write_b128 v38, v[32:35] offset:52224
	v_cvt_pk_bf16_f32 v32, v56, v57
	v_cvt_pk_bf16_f32 v33, v58, v59
	v_cvt_pk_bf16_f32 v34, v42, v43
	v_cvt_pk_bf16_f32 v35, v62, v63
	v_and_b32_e32 v45, 0xffff0000, v110
	v_and_b32_e32 v104, 0xffff0000, v112
	v_and_b32_e32 v74, 0xffff0000, v114
	v_and_b32_e32 v160, 0xffff0000, v116
	v_and_b32_e32 v102, 0xffff0000, v118
	v_and_b32_e32 v162, 0xffff0000, v120
	v_and_b32_e32 v165, 0xffff0000, v122
	v_and_b32_e32 v170, 0xffff0000, v124
	ds_write_b128 v38, v[32:35] offset:52368
	v_cvt_pk_bf16_f32 v32, v37, v103
	v_cvt_pk_bf16_f32 v33, v73, v107
	v_cvt_pk_bf16_f32 v34, v72, v161
	v_cvt_pk_bf16_f32 v35, v106, v169
	v_add_u32_e32 v37, s58, v127
	ds_write_b128 v37, v[32:35]
	v_cvt_pk_bf16_f32 v32, v45, v104
	v_cvt_pk_bf16_f32 v33, v74, v160
	v_cvt_pk_bf16_f32 v34, v102, v162
	v_cvt_pk_bf16_f32 v35, v165, v170
	s_and_b64 vcc, exec, s[0:1]
	ds_write_b128 v37, v[32:35] offset:144
	s_cbranch_vccnz .LBB0_842
	v_mul_f32_e32 v32, 0x3fb8aa3b, v36
	v_mul_f32_e32 v33, 0x3fb8aa3b, v39
	v_exp_f32_e32 v32, v32
	v_exp_f32_e32 v33, v33
	v_add_u32_e32 v34, 0x21800, v44
	ds_write_b64 v34, v[32:33]
.LBB0_842:
	s_waitcnt vmcnt(1)
	v_mov_b64_e32 v[62:63], v[50:51]
	s_waitcnt vmcnt(0)
	v_mov_b64_e32 v[58:59], v[54:55]
	s_cmp_eq_u32 s86, 0x1e0000
	v_lshl_add_u64 v[102:103], v[96:97], 0, s[86:87]
	v_mov_b64_e32 v[60:61], v[48:49]
	v_mov_b64_e32 v[56:57], v[52:53]
	s_cbranch_scc1 .LBB0_844
	s_lshl_b64 s[52:53], s[84:85], 1
	s_add_u32 s32, s70, s52
	s_addc_u32 s33, s71, s53
	s_add_u32 s98, s62, s52
	s_addc_u32 s99, s63, s53
	s_add_u32 s52, s64, s52
	s_addc_u32 s53, s65, s53
	global_load_dword v240, v249, s[32:33] nt
	global_load_dword v241, v249, s[32:33] offset:2048 nt
	global_load_dword v242, v250, s[32:33] nt
	global_load_dword v243, v250, s[32:33] offset:2048 nt
	global_load_dword v244, v251, s[32:33] nt
	global_load_dword v245, v251, s[32:33] offset:2048 nt
	global_load_dword v246, v252, s[32:33] nt
	global_load_dword v247, v252, s[32:33] offset:2048 nt
	global_load_dword v110, v249, s[98:99] nt
	global_load_dword v111, v249, s[52:53] nt
	global_load_dword v112, v249, s[98:99] offset:2048 nt
	global_load_dword v113, v249, s[52:53] offset:2048 nt
	global_load_dword v114, v250, s[98:99] nt
	global_load_dword v115, v250, s[52:53] nt
	global_load_dword v116, v250, s[98:99] offset:2048 nt
	global_load_dword v117, v250, s[52:53] offset:2048 nt
	global_load_dword v118, v251, s[98:99] nt
	global_load_dword v119, v251, s[52:53] nt
	global_load_dword v120, v251, s[98:99] offset:2048 nt
	global_load_dword v121, v251, s[52:53] offset:2048 nt
	global_load_dword v122, v252, s[98:99] nt
	global_load_dword v123, v252, s[52:53] nt
	s_add_u32 s32, s92, s86
	s_addc_u32 s33, s93, s87
	s_add_u32 s32, s32, 0x13420000
	s_addc_u32 s33, s33, 0
	global_load_dwordx4 v[56:59], v253, s[32:33] nt
	global_load_dword v124, v252, s[98:99] offset:2048 nt
	global_load_dword v125, v252, s[52:53] offset:2048 nt
	global_load_dwordx4 v[60:63], v253, s[32:33] offset:16 nt
